# attention finalize: 16 serialized (gain load, wait, scale, store) steps de-serialised: all gain loads issued up front into dead registers, one wait
# speedup vs baseline: 1.0009x; 1.0009x over previous
; __device__ __forceinline__ void attn_unit(LAS unsigned char* lds, int b, int h, int qb, const bf16_t* Q, const bf16_t* KF, const bf16_t* VT,
;                                           const float* gout, bf16_t* MIXED, int wave, int lane) {
;     ...
;     const float lt = l_run + __shfl_xor(l_run, 32);
;     const float inv = 1.f / lt;
;     float ss = 0.f;
; #pragma unroll
;     for (int db = 0; db < 4; ++db)
; #pragma unroll
;         for (int i = 0; i < 16; ++i) { oacc[db][i] *= inv; ss += oacc[db][i] * oacc[db][i]; }
;     ss += __shfl_xor(ss, 32);
;     const float rstd = rsqrtf(ss * (1.f / 128.f) + EPS);
;     bf16_t* orow = MIXED + tokq * D + 1024 + h * 128;
; #pragma unroll
;     for (int db = 0; db < 4; ++db)
; #pragma unroll
;         for (int g4 = 0; g4 < 4; ++g4) {
;             const int dv0 = db * 32 + 8 * g4 + 4 * hi;
;             const f32x4 gv = *(const f32x4*)(gout + h * 128 + dv0);
.LBB0_402:
	v_cmp_lt_i32_e32 vcc, v221, v223
	v_lshlrev_b64 v[6:7], 12, v[208:209]
	s_mov_b32 s63, s77
	v_cndmask_b32_e32 v0, v222, v221, vcc
	v_lshlrev_b32_e32 v136, 2, v0
	ds_bpermute_b32 v0, v136, v96
	v_ashrrev_i32_e32 v211, 31, v210
	s_waitcnt lgkmcnt(0)
	s_barrier
	v_add_f32_e32 v0, v96, v0
	v_div_scale_f32 v1, s[4:5], v0, v0, 1.0
	v_rcp_f32_e32 v2, v1
	v_readlane_b32 s4, v235, 45
	v_readlane_b32 s5, v235, 46
	v_fma_f32 v3, -v1, v2, 1.0
	v_fmac_f32_e32 v2, v3, v2
	v_div_scale_f32 v3, vcc, 1.0, v0, 1.0
	v_mul_f32_e32 v4, v3, v2
	v_fma_f32 v5, -v1, v4, v3
	v_fmac_f32_e32 v4, v5, v2
	v_fma_f32 v1, -v1, v4, v3
	v_div_fmas_f32 v1, v1, v2, v4
	v_div_fixup_f32 v10, v1, v0, 1.0
	v_lshl_add_u64 v[6:7], s[4:5], 0, v[6:7]
	v_lshl_add_u64 v[8:9], v[6:7], 0, s[62:63]
	v_lshl_add_u64 v[6:7], v[210:211], 2, s[52:53]
	v_pk_mul_f32 v[64:65], v[64:65], v[10:11] op_sel_hi:[1,0]
	global_load_dwordx4 v[52:55], v[6:7], off
	global_load_dwordx4 v[140:143], v[6:7], off offset:32
	global_load_dwordx4 v[160:163], v[6:7], off offset:64
	global_load_dwordx4 v[164:167], v[6:7], off offset:96
	global_load_dwordx4 v[168:171], v[6:7], off offset:128
	global_load_dwordx4 v[172:175], v[6:7], off offset:160
	global_load_dwordx4 v[176:179], v[6:7], off offset:192
	global_load_dwordx4 v[180:183], v[6:7], off offset:224
	global_load_dwordx4 v[184:187], v[6:7], off offset:256
	global_load_dwordx4 v[188:191], v[6:7], off offset:288
	global_load_dwordx4 v[192:195], v[6:7], off offset:320
	global_load_dwordx4 v[196:199], v[6:7], off offset:352
	global_load_dwordx4 v[200:203], v[6:7], off offset:384
	global_load_dwordx4 v[220:223], v[6:7], off offset:416
	global_load_dwordx4 v[224:227], v[6:7], off offset:448
	global_load_dwordx4 v[228:231], v[6:7], off offset:480
	v_pk_mul_f32 v[60:61], v[66:67], v[10:11] op_sel_hi:[1,0]
	v_pk_mul_f32 v[66:67], v[64:65], v[64:65]
	v_pk_mul_f32 v[62:63], v[60:61], v[60:61]
	v_add_f32_e32 v66, v66, v67
	v_pk_mul_f32 v[68:69], v[68:69], v[10:11] op_sel_hi:[1,0]
	v_add_f32_e32 v62, v62, v66
	v_pk_mul_f32 v[98:99], v[68:69], v[68:69]
	v_add_f32_e32 v62, v63, v62
	v_pk_mul_f32 v[70:71], v[70:71], v[10:11] op_sel_hi:[1,0]
	v_add_f32_e32 v62, v98, v62
	v_pk_mul_f32 v[96:97], v[70:71], v[70:71]
	v_add_f32_e32 v62, v99, v62
	v_pk_mul_f32 v[72:73], v[72:73], v[10:11] op_sel_hi:[1,0]
	v_add_f32_e32 v62, v96, v62
	v_pk_mul_f32 v[102:103], v[72:73], v[72:73]
	v_add_f32_e32 v62, v97, v62
	v_pk_mul_f32 v[74:75], v[74:75], v[10:11] op_sel_hi:[1,0]
	v_add_f32_e32 v62, v102, v62
	v_pk_mul_f32 v[100:101], v[74:75], v[74:75]
	v_add_f32_e32 v62, v103, v62
	v_pk_mul_f32 v[76:77], v[76:77], v[10:11] op_sel_hi:[1,0]
	v_add_f32_e32 v62, v100, v62
	v_pk_mul_f32 v[106:107], v[76:77], v[76:77]
	v_add_f32_e32 v62, v101, v62
	v_pk_mul_f32 v[78:79], v[78:79], v[10:11] op_sel_hi:[1,0]
	v_add_f32_e32 v62, v106, v62
	v_pk_mul_f32 v[104:105], v[78:79], v[78:79]
	v_add_f32_e32 v62, v107, v62
	v_pk_mul_f32 v[80:81], v[80:81], v[10:11] op_sel_hi:[1,0]
	v_add_f32_e32 v62, v104, v62
	v_pk_mul_f32 v[108:109], v[80:81], v[80:81]
	v_add_f32_e32 v62, v105, v62
	v_pk_mul_f32 v[50:51], v[82:83], v[10:11] op_sel_hi:[1,0]
	v_add_f32_e32 v62, v108, v62
	v_pk_mul_f32 v[82:83], v[50:51], v[50:51]
	v_add_f32_e32 v62, v109, v62
	v_pk_mul_f32 v[48:49], v[84:85], v[10:11] op_sel_hi:[1,0]
	v_add_f32_e32 v62, v82, v62
	v_pk_mul_f32 v[84:85], v[48:49], v[48:49]
	v_add_f32_e32 v62, v83, v62
	v_pk_mul_f32 v[46:47], v[86:87], v[10:11] op_sel_hi:[1,0]
	v_add_f32_e32 v62, v84, v62
	v_pk_mul_f32 v[86:87], v[46:47], v[46:47]
	v_add_f32_e32 v62, v85, v62
	v_pk_mul_f32 v[44:45], v[88:89], v[10:11] op_sel_hi:[1,0]
	v_add_f32_e32 v62, v86, v62
	v_pk_mul_f32 v[88:89], v[44:45], v[44:45]
	v_add_f32_e32 v62, v87, v62
	v_pk_mul_f32 v[42:43], v[90:91], v[10:11] op_sel_hi:[1,0]
	v_add_f32_e32 v62, v88, v62
	v_pk_mul_f32 v[90:91], v[42:43], v[42:43]
	v_add_f32_e32 v62, v89, v62
	v_pk_mul_f32 v[40:41], v[92:93], v[10:11] op_sel_hi:[1,0]
	v_add_f32_e32 v62, v90, v62
	v_pk_mul_f32 v[92:93], v[40:41], v[40:41]
	v_add_f32_e32 v62, v91, v62
	v_pk_mul_f32 v[38:39], v[94:95], v[10:11] op_sel_hi:[1,0]
	v_add_f32_e32 v62, v92, v62
	v_pk_mul_f32 v[94:95], v[38:39], v[38:39]
	v_add_f32_e32 v62, v93, v62
	v_pk_mul_f32 v[36:37], v[112:113], v[10:11] op_sel_hi:[1,0]
	v_add_f32_e32 v62, v94, v62
	v_pk_mul_f32 v[112:113], v[36:37], v[36:37]
	v_add_f32_e32 v62, v95, v62
	v_pk_mul_f32 v[34:35], v[114:115], v[10:11] op_sel_hi:[1,0]
	v_add_f32_e32 v62, v112, v62
	v_pk_mul_f32 v[110:111], v[34:35], v[34:35]
	v_add_f32_e32 v62, v113, v62
	v_pk_mul_f32 v[32:33], v[116:117], v[10:11] op_sel_hi:[1,0]
	v_add_f32_e32 v62, v110, v62
	v_pk_mul_f32 v[116:117], v[32:33], v[32:33]
	v_add_f32_e32 v62, v111, v62
	v_pk_mul_f32 v[30:31], v[118:119], v[10:11] op_sel_hi:[1,0]
	v_add_f32_e32 v62, v116, v62
	v_pk_mul_f32 v[114:115], v[30:31], v[30:31]
	v_add_f32_e32 v62, v117, v62
	v_pk_mul_f32 v[28:29], v[120:121], v[10:11] op_sel_hi:[1,0]
	v_add_f32_e32 v62, v114, v62
	v_pk_mul_f32 v[120:121], v[28:29], v[28:29]
	v_add_f32_e32 v62, v115, v62
	v_pk_mul_f32 v[24:25], v[122:123], v[10:11] op_sel_hi:[1,0]
	v_add_f32_e32 v62, v120, v62
	v_pk_mul_f32 v[118:119], v[24:25], v[24:25]
	v_add_f32_e32 v62, v121, v62
	v_pk_mul_f32 v[22:23], v[124:125], v[10:11] op_sel_hi:[1,0]
	v_add_f32_e32 v62, v118, v62
	v_pk_mul_f32 v[124:125], v[22:23], v[22:23]
	v_add_f32_e32 v62, v119, v62
	v_pk_mul_f32 v[20:21], v[126:127], v[10:11] op_sel_hi:[1,0]
	v_add_f32_e32 v62, v124, v62
	v_pk_mul_f32 v[122:123], v[20:21], v[20:21]
	v_add_f32_e32 v62, v125, v62
	v_pk_mul_f32 v[18:19], v[144:145], v[10:11] op_sel_hi:[1,0]
	v_add_f32_e32 v62, v122, v62
	v_pk_mul_f32 v[128:129], v[18:19], v[18:19]
; __device__ __forceinline__ unsigned pk2(float lo, float hi) { f32x2 v = {lo, hi}; bf16x2_t b = __builtin_convertvector(v, bf16x2_t); return __builtin_bit_cast(unsigned, b); }
; __device__ __forceinline__ void attn_unit(LAS unsigned char* lds, int b, int h, int qb, const bf16_t* Q, const bf16_t* KF, const bf16_t* VT,
;                                           const float* gout, bf16_t* MIXED, int wave, int lane) {
;     ...
;         for (int i = 0; i < 16; ++i) { oacc[db][i] *= inv; ss += oacc[db][i] * oacc[db][i]; }
;     ss += __shfl_xor(ss, 32);
;     const float rstd = rsqrtf(ss * (1.f / 128.f) + EPS);
;     bf16_t* orow = MIXED + tokq * D + 1024 + h * 128;
; #pragma unroll
;     for (int db = 0; db < 4; ++db)
; #pragma unroll
;         for (int g4 = 0; g4 < 4; ++g4) {
;             const int dv0 = db * 32 + 8 * g4 + 4 * hi;
;             const f32x4 gv = *(const f32x4*)(gout + h * 128 + dv0);
;             u32x2 w; w.x = pk2(oacc[db][4 * g4 + 0] * rstd * gv.x, oacc[db][4 * g4 + 1] * rstd * gv.y);
;             w.y = pk2(oacc[db][4 * g4 + 2] * rstd * gv.z, oacc[db][4 * g4 + 3] * rstd * gv.w);
;             *(u32x2*)(orow + dv0) = w;
;         }
	v_add_f32_e32 v62, v123, v62
	v_pk_mul_f32 v[16:17], v[146:147], v[10:11] op_sel_hi:[1,0]
	v_add_f32_e32 v62, v128, v62
	v_pk_mul_f32 v[126:127], v[16:17], v[16:17]
	v_add_f32_e32 v62, v129, v62
	v_pk_mul_f32 v[14:15], v[148:149], v[10:11] op_sel_hi:[1,0]
	v_add_f32_e32 v62, v126, v62
	v_pk_mul_f32 v[132:133], v[14:15], v[14:15]
	v_add_f32_e32 v62, v127, v62
	v_pk_mul_f32 v[12:13], v[150:151], v[10:11] op_sel_hi:[1,0]
	v_add_f32_e32 v62, v132, v62
	v_pk_mul_f32 v[130:131], v[12:13], v[12:13]
	v_add_f32_e32 v62, v133, v62
	v_pk_mul_f32 v[4:5], v[154:155], v[10:11] op_sel_hi:[1,0]
	v_pk_mul_f32 v[0:1], v[156:157], v[10:11] op_sel_hi:[1,0]
	v_pk_mul_f32 v[2:3], v[158:159], v[10:11] op_sel_hi:[1,0]
	v_pk_mul_f32 v[10:11], v[152:153], v[10:11] op_sel_hi:[1,0]
	v_add_f32_e32 v62, v130, v62
	v_pk_mul_f32 v[134:135], v[10:11], v[10:11]
	v_add_f32_e32 v62, v131, v62
	v_add_f32_e32 v62, v134, v62
	v_pk_mul_f32 v[26:27], v[4:5], v[4:5]
	v_add_f32_e32 v62, v135, v62
	v_add_f32_e32 v26, v26, v62
	v_pk_mul_f32 v[56:57], v[0:1], v[0:1]
	v_add_f32_e32 v26, v27, v26
	v_add_f32_e32 v26, v56, v26
	v_pk_mul_f32 v[58:59], v[2:3], v[2:3]
	v_add_f32_e32 v26, v57, v26
	v_add_f32_e32 v26, v58, v26
	v_add_f32_e32 v26, v59, v26
	ds_bpermute_b32 v27, v136, v26
	v_lshl_add_u64 v[8:9], v[210:211], 1, v[8:9]
	v_readlane_b32 s4, v235, 1
	s_add_i32 s33, s33, s4
	s_add_i32 s68, s68, s4
	s_waitcnt lgkmcnt(0)
	v_add_f32_e32 v26, v26, v27
	v_fmamk_f32 v26, v26, 0x3c000000, v217
	v_cmp_gt_f32_e32 vcc, s88, v26
	v_mul_f32_e32 v27, 0x4b800000, v26
	s_cmpk_gt_i32 s33, 0x1ff
	v_cndmask_b32_e32 v26, v26, v27, vcc
	v_rsq_f32_e32 v26, v26
	v_readlane_b32 s5, v235, 2
	v_mul_f32_e32 v27, 0x45800000, v26
	v_cndmask_b32_e32 v26, v26, v27, vcc
	v_pk_mul_f32 v[56:57], v[64:65], v[26:27] op_sel_hi:[1,0]
	v_pk_mul_f32 v[50:51], v[50:51], v[26:27] op_sel_hi:[1,0]
	s_waitcnt vmcnt(0)
	v_pk_mul_f32 v[52:53], v[52:53], v[56:57]
	v_pk_mul_f32 v[56:57], v[60:61], v[26:27] op_sel_hi:[1,0]
	v_cvt_pk_bf16_f32 v52, v52, v53
	v_pk_mul_f32 v[54:55], v[54:55], v[56:57]
	v_pk_mul_f32 v[56:57], v[68:69], v[26:27] op_sel_hi:[1,0]
	v_cvt_pk_bf16_f32 v53, v54, v55
	global_store_dwordx2 v[8:9], v[52:53], off offset:2048
	v_pk_mul_f32 v[48:49], v[48:49], v[26:27] op_sel_hi:[1,0]
	v_pk_mul_f32 v[46:47], v[46:47], v[26:27] op_sel_hi:[1,0]
	v_pk_mul_f32 v[44:45], v[44:45], v[26:27] op_sel_hi:[1,0]
	v_pk_mul_f32 v[42:43], v[42:43], v[26:27] op_sel_hi:[1,0]
	v_pk_mul_f32 v[40:41], v[40:41], v[26:27] op_sel_hi:[1,0]
	v_pk_mul_f32 v[38:39], v[38:39], v[26:27] op_sel_hi:[1,0]
	v_pk_mul_f32 v[36:37], v[36:37], v[26:27] op_sel_hi:[1,0]
	v_pk_mul_f32 v[34:35], v[34:35], v[26:27] op_sel_hi:[1,0]
	v_pk_mul_f32 v[32:33], v[32:33], v[26:27] op_sel_hi:[1,0]
	v_pk_mul_f32 v[30:31], v[30:31], v[26:27] op_sel_hi:[1,0]
	v_pk_mul_f32 v[28:29], v[28:29], v[26:27] op_sel_hi:[1,0]
	v_pk_mul_f32 v[24:25], v[24:25], v[26:27] op_sel_hi:[1,0]
	v_pk_mul_f32 v[22:23], v[22:23], v[26:27] op_sel_hi:[1,0]
	v_pk_mul_f32 v[20:21], v[20:21], v[26:27] op_sel_hi:[1,0]
	v_pk_mul_f32 v[18:19], v[18:19], v[26:27] op_sel_hi:[1,0]
	v_pk_mul_f32 v[16:17], v[16:17], v[26:27] op_sel_hi:[1,0]
	v_pk_mul_f32 v[14:15], v[14:15], v[26:27] op_sel_hi:[1,0]
	v_pk_mul_f32 v[12:13], v[12:13], v[26:27] op_sel_hi:[1,0]
	v_pk_mul_f32 v[10:11], v[10:11], v[26:27] op_sel_hi:[1,0]
	v_pk_mul_f32 v[4:5], v[4:5], v[26:27] op_sel_hi:[1,0]
	v_pk_mul_f32 v[0:1], v[0:1], v[26:27] op_sel_hi:[1,0]
	v_pk_mul_f32 v[2:3], v[2:3], v[26:27] op_sel_hi:[1,0]
	v_pk_mul_f32 v[52:53], v[140:141], v[56:57]
	v_pk_mul_f32 v[56:57], v[70:71], v[26:27] op_sel_hi:[1,0]
	v_cvt_pk_bf16_f32 v52, v52, v53
	v_pk_mul_f32 v[54:55], v[142:143], v[56:57]
	v_pk_mul_f32 v[56:57], v[72:73], v[26:27] op_sel_hi:[1,0]
	v_cvt_pk_bf16_f32 v53, v54, v55
	global_store_dwordx2 v[8:9], v[52:53], off offset:2064
	v_pk_mul_f32 v[52:53], v[160:161], v[56:57]
	v_pk_mul_f32 v[56:57], v[74:75], v[26:27] op_sel_hi:[1,0]
	v_cvt_pk_bf16_f32 v52, v52, v53
	v_pk_mul_f32 v[54:55], v[162:163], v[56:57]
	v_pk_mul_f32 v[56:57], v[76:77], v[26:27] op_sel_hi:[1,0]
	v_cvt_pk_bf16_f32 v53, v54, v55
	global_store_dwordx2 v[8:9], v[52:53], off offset:2080
	v_pk_mul_f32 v[52:53], v[164:165], v[56:57]
	v_pk_mul_f32 v[56:57], v[78:79], v[26:27] op_sel_hi:[1,0]
	v_cvt_pk_bf16_f32 v52, v52, v53
	v_pk_mul_f32 v[54:55], v[166:167], v[56:57]
	v_pk_mul_f32 v[56:57], v[80:81], v[26:27] op_sel_hi:[1,0]
	v_cvt_pk_bf16_f32 v53, v54, v55
	global_store_dwordx2 v[8:9], v[52:53], off offset:2096
	v_pk_mul_f32 v[52:53], v[168:169], v[56:57]
	v_pk_mul_f32 v[50:51], v[170:171], v[50:51]
	v_cvt_pk_bf16_f32 v52, v52, v53
	v_cvt_pk_bf16_f32 v53, v50, v51
	global_store_dwordx2 v[8:9], v[52:53], off offset:2112
	v_pk_mul_f32 v[48:49], v[172:173], v[48:49]
	v_pk_mul_f32 v[46:47], v[174:175], v[46:47]
	v_cvt_pk_bf16_f32 v48, v48, v49
	v_cvt_pk_bf16_f32 v49, v46, v47
	global_store_dwordx2 v[8:9], v[48:49], off offset:2128
	v_pk_mul_f32 v[44:45], v[176:177], v[44:45]
	v_pk_mul_f32 v[42:43], v[178:179], v[42:43]
	v_cvt_pk_bf16_f32 v44, v44, v45
	v_cvt_pk_bf16_f32 v45, v42, v43
	global_store_dwordx2 v[8:9], v[44:45], off offset:2144
	v_pk_mul_f32 v[40:41], v[180:181], v[40:41]
	v_pk_mul_f32 v[38:39], v[182:183], v[38:39]
	v_cvt_pk_bf16_f32 v40, v40, v41
	v_cvt_pk_bf16_f32 v41, v38, v39
	global_store_dwordx2 v[8:9], v[40:41], off offset:2160
	v_pk_mul_f32 v[36:37], v[184:185], v[36:37]
	v_pk_mul_f32 v[34:35], v[186:187], v[34:35]
	v_cvt_pk_bf16_f32 v36, v36, v37
	v_cvt_pk_bf16_f32 v37, v34, v35
	global_store_dwordx2 v[8:9], v[36:37], off offset:2176
	v_pk_mul_f32 v[32:33], v[188:189], v[32:33]
	v_pk_mul_f32 v[30:31], v[190:191], v[30:31]
	v_cvt_pk_bf16_f32 v32, v32, v33
	v_cvt_pk_bf16_f32 v33, v30, v31
	global_store_dwordx2 v[8:9], v[32:33], off offset:2192
	v_pk_mul_f32 v[28:29], v[192:193], v[28:29]
	v_pk_mul_f32 v[24:25], v[194:195], v[24:25]
	v_cvt_pk_bf16_f32 v28, v28, v29
	v_cvt_pk_bf16_f32 v29, v24, v25
	global_store_dwordx2 v[8:9], v[28:29], off offset:2208
	v_pk_mul_f32 v[22:23], v[196:197], v[22:23]
	v_pk_mul_f32 v[20:21], v[198:199], v[20:21]
	v_cvt_pk_bf16_f32 v22, v22, v23
	v_cvt_pk_bf16_f32 v23, v20, v21
	global_store_dwordx2 v[8:9], v[22:23], off offset:2224
	v_pk_mul_f32 v[18:19], v[200:201], v[18:19]
	v_pk_mul_f32 v[16:17], v[202:203], v[16:17]
	v_cvt_pk_bf16_f32 v18, v18, v19
	v_cvt_pk_bf16_f32 v19, v16, v17
	global_store_dwordx2 v[8:9], v[18:19], off offset:2240
	v_pk_mul_f32 v[14:15], v[220:221], v[14:15]
	v_pk_mul_f32 v[12:13], v[222:223], v[12:13]
	v_cvt_pk_bf16_f32 v14, v14, v15
	v_cvt_pk_bf16_f32 v15, v12, v13
	global_store_dwordx2 v[8:9], v[14:15], off offset:2256
	v_pk_mul_f32 v[10:11], v[224:225], v[10:11]
	v_pk_mul_f32 v[4:5], v[226:227], v[4:5]
	v_cvt_pk_bf16_f32 v10, v10, v11
	v_cvt_pk_bf16_f32 v11, v4, v5
	global_store_dwordx2 v[8:9], v[10:11], off offset:2272
	v_pk_mul_f32 v[0:1], v[228:229], v[0:1]
	v_pk_mul_f32 v[2:3], v[230:231], v[2:3]
	v_cvt_pk_bf16_f32 v0, v0, v1
	v_cvt_pk_bf16_f32 v1, v2, v3
	global_store_dwordx2 v[8:9], v[0:1], off offset:2288
	s_cbranch_scc1 .LBB0_535

; __device__ __forceinline__ void attn_unit(LAS unsigned char* lds, int b, int h, int qb, const bf16_t* Q, const bf16_t* KF, const bf16_t* VT,
;                                           const float* gout, bf16_t* MIXED, int wave, int lane) {
;     ...
;     const float lt = l_run + __shfl_xor(l_run, 32);
;     const float inv = 1.f / lt;
;     float ss = 0.f;
; #pragma unroll
;     for (int db = 0; db < 4; ++db)
; #pragma unroll
;         for (int i = 0; i < 16; ++i) { oacc[db][i] *= inv; ss += oacc[db][i] * oacc[db][i]; }
;     ss += __shfl_xor(ss, 32);
;     const float rstd = rsqrtf(ss * (1.f / 128.f) + EPS);
;     bf16_t* orow = MIXED + tokq * D + 1024 + h * 128;
; #pragma unroll
;     for (int db = 0; db < 4; ++db)
; #pragma unroll
;         for (int g4 = 0; g4 < 4; ++g4) {
;             const int dv0 = db * 32 + 8 * g4 + 4 * hi;
;             const f32x4 gv = *(const f32x4*)(gout + h * 128 + dv0);
.LBB0_469:
	v_cmp_lt_i32_e32 vcc, v222, v223
	v_readlane_b32 s16, v235, 45
	v_lshlrev_b64 v[6:7], 12, v[208:209]
	v_cndmask_b32_e32 v0, v221, v222, vcc
	v_lshlrev_b32_e32 v136, 2, v0
	ds_bpermute_b32 v0, v136, v114
	v_readlane_b32 s17, v235, 46
	s_lshl_b32 s62, s35, 1
	s_mov_b32 s63, s77
	v_lshl_add_u64 v[6:7], s[16:17], 0, v[6:7]
	s_waitcnt lgkmcnt(0)
	v_add_f32_e32 v0, v114, v0
	v_div_scale_f32 v1, s[52:53], v0, v0, 1.0
	v_rcp_f32_e32 v2, v1
	v_readlane_b32 s16, v235, 21
	s_lshl_b32 s52, s35, 2
	v_readlane_b32 s22, v235, 27
	v_fma_f32 v3, -v1, v2, 1.0
	v_fmac_f32_e32 v2, v3, v2
	v_div_scale_f32 v3, vcc, 1.0, v0, 1.0
	v_mul_f32_e32 v4, v3, v2
	v_fma_f32 v5, -v1, v4, v3
	v_fmac_f32_e32 v4, v5, v2
	v_fma_f32 v1, -v1, v4, v3
	v_div_fmas_f32 v1, v1, v2, v4
	v_readlane_b32 s23, v235, 28
	s_add_u32 s52, s22, s52
	v_div_fixup_f32 v10, v1, v0, 1.0
	s_addc_u32 s53, s23, 0
	v_ashrrev_i32_e32 v211, 31, v210
	v_lshl_add_u64 v[8:9], v[6:7], 0, s[62:63]
	v_lshl_add_u64 v[6:7], v[210:211], 2, s[52:53]
	v_pk_mul_f32 v[64:65], v[64:65], v[10:11] op_sel_hi:[1,0]
	s_barrier
	global_load_dwordx4 v[52:55], v[6:7], off
	global_load_dwordx4 v[140:143], v[6:7], off offset:32
	global_load_dwordx4 v[160:163], v[6:7], off offset:64
	global_load_dwordx4 v[164:167], v[6:7], off offset:96
	global_load_dwordx4 v[168:171], v[6:7], off offset:128
	global_load_dwordx4 v[172:175], v[6:7], off offset:160
	global_load_dwordx4 v[176:179], v[6:7], off offset:192
	global_load_dwordx4 v[180:183], v[6:7], off offset:224
	global_load_dwordx4 v[184:187], v[6:7], off offset:256
	global_load_dwordx4 v[188:191], v[6:7], off offset:288
	global_load_dwordx4 v[192:195], v[6:7], off offset:320
	global_load_dwordx4 v[196:199], v[6:7], off offset:352
	global_load_dwordx4 v[200:203], v[6:7], off offset:384
	global_load_dwordx4 v[220:223], v[6:7], off offset:416
	global_load_dwordx4 v[224:227], v[6:7], off offset:448
	global_load_dwordx4 v[228:231], v[6:7], off offset:480
	v_pk_mul_f32 v[60:61], v[66:67], v[10:11] op_sel_hi:[1,0]
	v_pk_mul_f32 v[66:67], v[64:65], v[64:65]
	v_pk_mul_f32 v[62:63], v[60:61], v[60:61]
	v_add_f32_e32 v66, v66, v67
	v_pk_mul_f32 v[68:69], v[68:69], v[10:11] op_sel_hi:[1,0]
	v_add_f32_e32 v62, v62, v66
	v_pk_mul_f32 v[114:115], v[68:69], v[68:69]
	v_add_f32_e32 v62, v63, v62
	v_pk_mul_f32 v[70:71], v[70:71], v[10:11] op_sel_hi:[1,0]
	v_add_f32_e32 v62, v114, v62
	v_pk_mul_f32 v[112:113], v[70:71], v[70:71]
	v_add_f32_e32 v62, v115, v62
	v_pk_mul_f32 v[72:73], v[72:73], v[10:11] op_sel_hi:[1,0]
	v_add_f32_e32 v62, v112, v62
	v_pk_mul_f32 v[118:119], v[72:73], v[72:73]
	v_add_f32_e32 v62, v113, v62
	v_pk_mul_f32 v[74:75], v[74:75], v[10:11] op_sel_hi:[1,0]
	v_add_f32_e32 v62, v118, v62
	v_pk_mul_f32 v[116:117], v[74:75], v[74:75]
	v_add_f32_e32 v62, v119, v62
	v_pk_mul_f32 v[76:77], v[76:77], v[10:11] op_sel_hi:[1,0]
	v_add_f32_e32 v62, v116, v62
	v_pk_mul_f32 v[122:123], v[76:77], v[76:77]
	v_add_f32_e32 v62, v117, v62
	v_pk_mul_f32 v[78:79], v[78:79], v[10:11] op_sel_hi:[1,0]
	v_add_f32_e32 v62, v122, v62
	v_pk_mul_f32 v[120:121], v[78:79], v[78:79]
	v_add_f32_e32 v62, v123, v62
	v_pk_mul_f32 v[80:81], v[80:81], v[10:11] op_sel_hi:[1,0]
	v_add_f32_e32 v62, v120, v62
	v_pk_mul_f32 v[124:125], v[80:81], v[80:81]
	v_add_f32_e32 v62, v121, v62
	v_pk_mul_f32 v[50:51], v[82:83], v[10:11] op_sel_hi:[1,0]
	v_add_f32_e32 v62, v124, v62
	v_pk_mul_f32 v[82:83], v[50:51], v[50:51]
	v_add_f32_e32 v62, v125, v62
	v_pk_mul_f32 v[48:49], v[84:85], v[10:11] op_sel_hi:[1,0]
	v_add_f32_e32 v62, v82, v62
	v_pk_mul_f32 v[84:85], v[48:49], v[48:49]
	v_add_f32_e32 v62, v83, v62
	v_pk_mul_f32 v[46:47], v[86:87], v[10:11] op_sel_hi:[1,0]
	v_add_f32_e32 v62, v84, v62
	v_pk_mul_f32 v[86:87], v[46:47], v[46:47]
	v_add_f32_e32 v62, v85, v62
	v_pk_mul_f32 v[44:45], v[88:89], v[10:11] op_sel_hi:[1,0]
	v_add_f32_e32 v62, v86, v62
	v_pk_mul_f32 v[88:89], v[44:45], v[44:45]
	v_add_f32_e32 v62, v87, v62
	v_pk_mul_f32 v[42:43], v[90:91], v[10:11] op_sel_hi:[1,0]
	v_add_f32_e32 v62, v88, v62
	v_pk_mul_f32 v[90:91], v[42:43], v[42:43]
	v_add_f32_e32 v62, v89, v62
	v_pk_mul_f32 v[40:41], v[92:93], v[10:11] op_sel_hi:[1,0]
	v_add_f32_e32 v62, v90, v62
	v_pk_mul_f32 v[92:93], v[40:41], v[40:41]
	v_add_f32_e32 v62, v91, v62
	v_pk_mul_f32 v[38:39], v[94:95], v[10:11] op_sel_hi:[1,0]
	v_add_f32_e32 v62, v92, v62
	v_pk_mul_f32 v[94:95], v[38:39], v[38:39]
	v_add_f32_e32 v62, v93, v62
	v_pk_mul_f32 v[36:37], v[96:97], v[10:11] op_sel_hi:[1,0]
	v_add_f32_e32 v62, v94, v62
	v_pk_mul_f32 v[96:97], v[36:37], v[36:37]
	v_add_f32_e32 v62, v95, v62
	v_pk_mul_f32 v[34:35], v[98:99], v[10:11] op_sel_hi:[1,0]
	v_add_f32_e32 v62, v96, v62
	v_pk_mul_f32 v[98:99], v[34:35], v[34:35]
	v_add_f32_e32 v62, v97, v62
	v_pk_mul_f32 v[32:33], v[100:101], v[10:11] op_sel_hi:[1,0]
	v_add_f32_e32 v62, v98, v62
	v_pk_mul_f32 v[100:101], v[32:33], v[32:33]
	v_add_f32_e32 v62, v99, v62
	v_pk_mul_f32 v[30:31], v[102:103], v[10:11] op_sel_hi:[1,0]
	v_add_f32_e32 v62, v100, v62
	v_pk_mul_f32 v[102:103], v[30:31], v[30:31]
	v_add_f32_e32 v62, v101, v62
	v_pk_mul_f32 v[28:29], v[104:105], v[10:11] op_sel_hi:[1,0]
	v_add_f32_e32 v62, v102, v62
	v_pk_mul_f32 v[104:105], v[28:29], v[28:29]
	v_add_f32_e32 v62, v103, v62
	v_pk_mul_f32 v[24:25], v[106:107], v[10:11] op_sel_hi:[1,0]
	v_add_f32_e32 v62, v104, v62
	v_pk_mul_f32 v[106:107], v[24:25], v[24:25]
	v_add_f32_e32 v62, v105, v62
	v_pk_mul_f32 v[22:23], v[108:109], v[10:11] op_sel_hi:[1,0]
	v_add_f32_e32 v62, v106, v62
	v_pk_mul_f32 v[108:109], v[22:23], v[22:23]
	v_add_f32_e32 v62, v107, v62
	v_pk_mul_f32 v[20:21], v[110:111], v[10:11] op_sel_hi:[1,0]
	v_add_f32_e32 v62, v108, v62
; __device__ __forceinline__ unsigned pk2(float lo, float hi) { f32x2 v = {lo, hi}; bf16x2_t b = __builtin_convertvector(v, bf16x2_t); return __builtin_bit_cast(unsigned, b); }
; __device__ __forceinline__ void attn_unit(LAS unsigned char* lds, int b, int h, int qb, const bf16_t* Q, const bf16_t* KF, const bf16_t* VT,
;                                           const float* gout, bf16_t* MIXED, int wave, int lane) {
;     ...
;         for (int i = 0; i < 16; ++i) { oacc[db][i] *= inv; ss += oacc[db][i] * oacc[db][i]; }
;     ss += __shfl_xor(ss, 32);
;     const float rstd = rsqrtf(ss * (1.f / 128.f) + EPS);
;     bf16_t* orow = MIXED + tokq * D + 1024 + h * 128;
; #pragma unroll
;     for (int db = 0; db < 4; ++db)
; #pragma unroll
;         for (int g4 = 0; g4 < 4; ++g4) {
;             const int dv0 = db * 32 + 8 * g4 + 4 * hi;
;             const f32x4 gv = *(const f32x4*)(gout + h * 128 + dv0);
;             u32x2 w; w.x = pk2(oacc[db][4 * g4 + 0] * rstd * gv.x, oacc[db][4 * g4 + 1] * rstd * gv.y);
;             w.y = pk2(oacc[db][4 * g4 + 2] * rstd * gv.z, oacc[db][4 * g4 + 3] * rstd * gv.w);
;             *(u32x2*)(orow + dv0) = w;
;         }
	v_pk_mul_f32 v[110:111], v[20:21], v[20:21]
	v_add_f32_e32 v62, v109, v62
	v_pk_mul_f32 v[18:19], v[144:145], v[10:11] op_sel_hi:[1,0]
	v_add_f32_e32 v62, v110, v62
	v_pk_mul_f32 v[128:129], v[18:19], v[18:19]
	v_add_f32_e32 v62, v111, v62
	v_pk_mul_f32 v[16:17], v[146:147], v[10:11] op_sel_hi:[1,0]
	v_add_f32_e32 v62, v128, v62
	v_pk_mul_f32 v[126:127], v[16:17], v[16:17]
	v_add_f32_e32 v62, v129, v62
	v_pk_mul_f32 v[14:15], v[148:149], v[10:11] op_sel_hi:[1,0]
	v_add_f32_e32 v62, v126, v62
	v_pk_mul_f32 v[132:133], v[14:15], v[14:15]
	v_add_f32_e32 v62, v127, v62
	v_pk_mul_f32 v[12:13], v[150:151], v[10:11] op_sel_hi:[1,0]
	v_add_f32_e32 v62, v132, v62
	v_pk_mul_f32 v[130:131], v[12:13], v[12:13]
	v_add_f32_e32 v62, v133, v62
	v_pk_mul_f32 v[4:5], v[154:155], v[10:11] op_sel_hi:[1,0]
	v_pk_mul_f32 v[0:1], v[156:157], v[10:11] op_sel_hi:[1,0]
	v_pk_mul_f32 v[2:3], v[158:159], v[10:11] op_sel_hi:[1,0]
	v_pk_mul_f32 v[10:11], v[152:153], v[10:11] op_sel_hi:[1,0]
	v_add_f32_e32 v62, v130, v62
	v_pk_mul_f32 v[134:135], v[10:11], v[10:11]
	v_add_f32_e32 v62, v131, v62
	v_add_f32_e32 v62, v134, v62
	v_pk_mul_f32 v[26:27], v[4:5], v[4:5]
	v_add_f32_e32 v62, v135, v62
	v_add_f32_e32 v26, v26, v62
	v_pk_mul_f32 v[56:57], v[0:1], v[0:1]
	v_add_f32_e32 v26, v27, v26
	v_add_f32_e32 v26, v56, v26
	v_pk_mul_f32 v[58:59], v[2:3], v[2:3]
	v_add_f32_e32 v26, v57, v26
	v_add_f32_e32 v26, v58, v26
	v_add_f32_e32 v26, v59, v26
	ds_bpermute_b32 v27, v136, v26
	v_lshl_add_u64 v[8:9], v[210:211], 1, v[8:9]
	s_lshl_b32 s63, s60, 8
	v_readlane_b32 s28, v235, 33
	s_add_i32 s63, s63, s56
	s_waitcnt lgkmcnt(0)
	v_add_f32_e32 v26, v26, v27
	v_fmamk_f32 v26, v26, 0x3c000000, v217
	v_cmp_gt_f32_e32 vcc, s88, v26
	v_mul_f32_e32 v27, 0x4b800000, v26
	s_mov_b32 s28, s56
	v_cndmask_b32_e32 v26, v26, v27, vcc
	v_rsq_f32_e32 v26, v26
	v_readlane_b32 s56, v235, 49
	v_readlane_b32 s57, v235, 50
	v_readlane_b32 s29, v235, 34
	v_mul_f32_e32 v27, 0x45800000, v26
	v_cndmask_b32_e32 v26, v26, v27, vcc
	v_pk_mul_f32 v[56:57], v[64:65], v[26:27] op_sel_hi:[1,0]
	v_pk_mul_f32 v[50:51], v[50:51], v[26:27] op_sel_hi:[1,0]
	s_waitcnt vmcnt(0)
	v_pk_mul_f32 v[52:53], v[52:53], v[56:57]
	v_pk_mul_f32 v[56:57], v[60:61], v[26:27] op_sel_hi:[1,0]
	v_cvt_pk_bf16_f32 v52, v52, v53
	v_pk_mul_f32 v[54:55], v[54:55], v[56:57]
	v_pk_mul_f32 v[56:57], v[68:69], v[26:27] op_sel_hi:[1,0]
	v_cvt_pk_bf16_f32 v53, v54, v55
	global_store_dwordx2 v[8:9], v[52:53], off offset:2048
	v_pk_mul_f32 v[48:49], v[48:49], v[26:27] op_sel_hi:[1,0]
	v_pk_mul_f32 v[46:47], v[46:47], v[26:27] op_sel_hi:[1,0]
	v_pk_mul_f32 v[44:45], v[44:45], v[26:27] op_sel_hi:[1,0]
	v_pk_mul_f32 v[42:43], v[42:43], v[26:27] op_sel_hi:[1,0]
	v_pk_mul_f32 v[40:41], v[40:41], v[26:27] op_sel_hi:[1,0]
	v_pk_mul_f32 v[38:39], v[38:39], v[26:27] op_sel_hi:[1,0]
	v_pk_mul_f32 v[36:37], v[36:37], v[26:27] op_sel_hi:[1,0]
	v_pk_mul_f32 v[34:35], v[34:35], v[26:27] op_sel_hi:[1,0]
	v_pk_mul_f32 v[32:33], v[32:33], v[26:27] op_sel_hi:[1,0]
	v_pk_mul_f32 v[30:31], v[30:31], v[26:27] op_sel_hi:[1,0]
	v_pk_mul_f32 v[28:29], v[28:29], v[26:27] op_sel_hi:[1,0]
	v_pk_mul_f32 v[24:25], v[24:25], v[26:27] op_sel_hi:[1,0]
	v_pk_mul_f32 v[22:23], v[22:23], v[26:27] op_sel_hi:[1,0]
	v_pk_mul_f32 v[20:21], v[20:21], v[26:27] op_sel_hi:[1,0]
	v_pk_mul_f32 v[18:19], v[18:19], v[26:27] op_sel_hi:[1,0]
	v_pk_mul_f32 v[16:17], v[16:17], v[26:27] op_sel_hi:[1,0]
	v_pk_mul_f32 v[14:15], v[14:15], v[26:27] op_sel_hi:[1,0]
	v_pk_mul_f32 v[12:13], v[12:13], v[26:27] op_sel_hi:[1,0]
	v_pk_mul_f32 v[10:11], v[10:11], v[26:27] op_sel_hi:[1,0]
	v_pk_mul_f32 v[4:5], v[4:5], v[26:27] op_sel_hi:[1,0]
	v_pk_mul_f32 v[0:1], v[0:1], v[26:27] op_sel_hi:[1,0]
	v_pk_mul_f32 v[2:3], v[2:3], v[26:27] op_sel_hi:[1,0]
	v_readlane_b32 s30, v235, 35
	v_readlane_b32 s31, v235, 36
	s_mov_b64 s[30:31], s[70:71]
	s_and_b64 vcc, exec, s[70:71]
	s_mov_b32 s29, s80
	s_mov_b32 s81, 0x38e38e39
	v_readlane_b32 s17, v235, 22
	v_readlane_b32 s18, v235, 23
	v_readlane_b32 s19, v235, 24
	v_readlane_b32 s20, v235, 25
	v_readlane_b32 s21, v235, 26
	v_readlane_b32 s24, v235, 29
	v_readlane_b32 s25, v235, 30
	v_readlane_b32 s26, v235, 31
	v_readlane_b32 s27, v235, 32
	v_pk_mul_f32 v[52:53], v[140:141], v[56:57]
	v_pk_mul_f32 v[56:57], v[70:71], v[26:27] op_sel_hi:[1,0]
	v_cvt_pk_bf16_f32 v52, v52, v53
	v_pk_mul_f32 v[54:55], v[142:143], v[56:57]
	v_pk_mul_f32 v[56:57], v[72:73], v[26:27] op_sel_hi:[1,0]
	v_cvt_pk_bf16_f32 v53, v54, v55
	global_store_dwordx2 v[8:9], v[52:53], off offset:2064
	v_pk_mul_f32 v[52:53], v[160:161], v[56:57]
	v_pk_mul_f32 v[56:57], v[74:75], v[26:27] op_sel_hi:[1,0]
; __device__ __forceinline__ unsigned pk2(float lo, float hi) { f32x2 v = {lo, hi}; bf16x2_t b = __builtin_convertvector(v, bf16x2_t); return __builtin_bit_cast(unsigned, b); }
; __device__ __forceinline__ void attn_unit(LAS unsigned char* lds, int b, int h, int qb, const bf16_t* Q, const bf16_t* KF, const bf16_t* VT,
;                                           const float* gout, bf16_t* MIXED, int wave, int lane) {
;     ...
;     bf16x8 qf[12];
; #pragma unroll
;     for (int ks = 0; ks < 12; ++ks) qf[ks] = *(const bf16x8*)(Q + tokq * 1536 + h * 192 + ks * 16 + hi * 8);
;     unsigned goff[6];
; #pragma unroll
;     for (int i = 0; i < 6; ++i) {
;         const int n = wave + 8 * i;
;         if (n < 25) { const int sl = n * 64 + lane, row = sl / 25, c = sl % 25; goff[i] = (unsigned)(((size_t)b * SEQ + row) * 1536 + h * 192 + (c < 24 ? c : 0) * 8); }
;         else { const int sl = (n - 25) * 64 + lane, dv = sl / 9, c = sl % 9; goff[i] = (unsigned)((size_t)(h * 128 + dv) * T + (size_t)b * SEQ + (c < 8 ? c : 0) * 8); }
;     ...
; #pragma unroll
;     for (int db = 0; db < 4; ++db)
; #pragma unroll
;         for (int g4 = 0; g4 < 4; ++g4) {
;             const int dv0 = db * 32 + 8 * g4 + 4 * hi;
;             const f32x4 gv = *(const f32x4*)(gout + h * 128 + dv0);
;             u32x2 w; w.x = pk2(oacc[db][4 * g4 + 0] * rstd * gv.x, oacc[db][4 * g4 + 1] * rstd * gv.y);
;             w.y = pk2(oacc[db][4 * g4 + 2] * rstd * gv.z, oacc[db][4 * g4 + 3] * rstd * gv.w);
;             *(u32x2*)(orow + dv0) = w;
;         }
	v_cvt_pk_bf16_f32 v52, v52, v53
	v_pk_mul_f32 v[54:55], v[162:163], v[56:57]
	v_pk_mul_f32 v[56:57], v[76:77], v[26:27] op_sel_hi:[1,0]
	v_cvt_pk_bf16_f32 v53, v54, v55
	global_store_dwordx2 v[8:9], v[52:53], off offset:2080
	v_pk_mul_f32 v[52:53], v[164:165], v[56:57]
	v_pk_mul_f32 v[56:57], v[78:79], v[26:27] op_sel_hi:[1,0]
	v_cvt_pk_bf16_f32 v52, v52, v53
	v_pk_mul_f32 v[54:55], v[166:167], v[56:57]
	v_pk_mul_f32 v[56:57], v[80:81], v[26:27] op_sel_hi:[1,0]
	v_cvt_pk_bf16_f32 v53, v54, v55
	global_store_dwordx2 v[8:9], v[52:53], off offset:2096
	v_pk_mul_f32 v[52:53], v[168:169], v[56:57]
	v_pk_mul_f32 v[50:51], v[170:171], v[50:51]
	v_cvt_pk_bf16_f32 v52, v52, v53
	v_cvt_pk_bf16_f32 v53, v50, v51
	global_store_dwordx2 v[8:9], v[52:53], off offset:2112
	v_pk_mul_f32 v[48:49], v[172:173], v[48:49]
	v_pk_mul_f32 v[46:47], v[174:175], v[46:47]
	v_cvt_pk_bf16_f32 v48, v48, v49
	v_cvt_pk_bf16_f32 v49, v46, v47
	global_store_dwordx2 v[8:9], v[48:49], off offset:2128
	v_pk_mul_f32 v[44:45], v[176:177], v[44:45]
	v_pk_mul_f32 v[42:43], v[178:179], v[42:43]
	v_cvt_pk_bf16_f32 v44, v44, v45
	v_cvt_pk_bf16_f32 v45, v42, v43
	global_store_dwordx2 v[8:9], v[44:45], off offset:2144
	v_pk_mul_f32 v[40:41], v[180:181], v[40:41]
	v_pk_mul_f32 v[38:39], v[182:183], v[38:39]
	v_cvt_pk_bf16_f32 v40, v40, v41
	v_cvt_pk_bf16_f32 v41, v38, v39
	global_store_dwordx2 v[8:9], v[40:41], off offset:2160
	v_pk_mul_f32 v[36:37], v[184:185], v[36:37]
	v_pk_mul_f32 v[34:35], v[186:187], v[34:35]
	v_cvt_pk_bf16_f32 v36, v36, v37
	v_cvt_pk_bf16_f32 v37, v34, v35
	global_store_dwordx2 v[8:9], v[36:37], off offset:2176
	v_pk_mul_f32 v[32:33], v[188:189], v[32:33]
	v_pk_mul_f32 v[30:31], v[190:191], v[30:31]
	v_cvt_pk_bf16_f32 v32, v32, v33
	v_cvt_pk_bf16_f32 v33, v30, v31
	global_store_dwordx2 v[8:9], v[32:33], off offset:2192
	v_pk_mul_f32 v[28:29], v[192:193], v[28:29]
	v_pk_mul_f32 v[24:25], v[194:195], v[24:25]
	v_cvt_pk_bf16_f32 v28, v28, v29
	v_cvt_pk_bf16_f32 v29, v24, v25
	global_store_dwordx2 v[8:9], v[28:29], off offset:2208
	v_pk_mul_f32 v[22:23], v[196:197], v[22:23]
	v_pk_mul_f32 v[20:21], v[198:199], v[20:21]
	v_cvt_pk_bf16_f32 v22, v22, v23
	v_cvt_pk_bf16_f32 v23, v20, v21
	global_store_dwordx2 v[8:9], v[22:23], off offset:2224
	v_pk_mul_f32 v[18:19], v[200:201], v[18:19]
	v_pk_mul_f32 v[16:17], v[202:203], v[16:17]
	v_cvt_pk_bf16_f32 v18, v18, v19
	v_cvt_pk_bf16_f32 v19, v16, v17
	global_store_dwordx2 v[8:9], v[18:19], off offset:2240
	v_pk_mul_f32 v[14:15], v[220:221], v[14:15]
	v_pk_mul_f32 v[12:13], v[222:223], v[12:13]
	v_cvt_pk_bf16_f32 v14, v14, v15
	v_cvt_pk_bf16_f32 v15, v12, v13
	global_store_dwordx2 v[8:9], v[14:15], off offset:2256
	v_pk_mul_f32 v[10:11], v[224:225], v[10:11]
	v_pk_mul_f32 v[4:5], v[226:227], v[4:5]
	v_cvt_pk_bf16_f32 v10, v10, v11
	v_cvt_pk_bf16_f32 v11, v4, v5
	global_store_dwordx2 v[8:9], v[10:11], off offset:2272
	v_pk_mul_f32 v[0:1], v[228:229], v[0:1]
	v_pk_mul_f32 v[2:3], v[230:231], v[2:3]
	v_cvt_pk_bf16_f32 v0, v0, v1
	v_cvt_pk_bf16_f32 v1, v2, v3
	v_mov_b32_e32 v2, v216
	global_store_dwordx2 v[8:9], v[0:1], off offset:2288
	v_mov_b64_e32 v[4:5], s[56:57]
	v_and_b32_e32 v0, 31, v2
	v_or_b32_e32 v212, s63, v0
	v_ashrrev_i32_e32 v213, 31, v212
	v_lshl_add_u64 v[208:209], s[54:55], 0, v[212:213]
	v_ashrrev_i32_e32 v1, 5, v2
	v_mad_u64_u32 v[4:5], s[60:61], v208, s59, v[4:5]
	v_mad_i32_i24 v5, v209, s59, v5
	v_lshlrev_b32_e32 v6, 3, v1
	v_lshl_add_u64 v[4:5], v[4:5], 0, s[76:77]
	v_ashrrev_i32_e32 v7, 31, v6
	v_lshl_add_u64 v[4:5], v[6:7], 1, v[4:5]
	global_load_dwordx4 v[128:131], v[4:5], off
	global_load_dwordx4 v[200:203], v[4:5], off offset:32
	global_load_dwordx4 v[196:199], v[4:5], off offset:64
	global_load_dwordx4 v[192:195], v[4:5], off offset:96
	global_load_dwordx4 v[188:191], v[4:5], off offset:128
	global_load_dwordx4 v[184:187], v[4:5], off offset:160
	global_load_dwordx4 v[180:183], v[4:5], off offset:192
	global_load_dwordx4 v[176:179], v[4:5], off offset:224
	global_load_dwordx4 v[172:175], v[4:5], off offset:256
	global_load_dwordx4 v[168:171], v[4:5], off offset:288
	global_load_dwordx4 v[164:167], v[4:5], off offset:320
	global_load_dwordx4 v[160:163], v[4:5], off offset:352
	v_add_u32_e32 v3, 0xfffff9c0, v2
	s_mov_b64 s[60:61], -1
	s_cbranch_vccz .LBB0_471
	v_add_u32_e32 v4, s29, v3
	v_mul_hi_i32 v5, v4, s81
	v_lshrrev_b32_e32 v6, 31, v5
	v_ashrrev_i32_e32 v5, 1, v5
	v_add_u32_e32 v5, v5, v6
	v_lshl_add_u32 v6, v5, 3, v5
	v_sub_u32_e32 v4, v4, v6
	v_lshlrev_b32_e32 v6, 3, v4
	v_cmp_gt_i32_e32 vcc, 8, v4
	v_add_lshl_u32 v5, v5, s35, 15
	s_mov_b64 s[60:61], 0
	v_cndmask_b32_e32 v4, 0, v6, vcc
	v_add3_u32 v96, v5, s54, v4
